# B item prologue: bias-table global loads unrolled (8 loads in flight, one wait) and LDS writes overlapped with Q loads
# speedup vs baseline: 1.0381x; 1.0030x over previous
;     ...
;     const int qb = 63 - (item >> 1), mp = item & 1;
;     const int b = xcd >> 2, h = xcd & 3;
;     for (int i = tid; i < 2048; i += NTHREADS) bias_lds[i] = p.biasB2[h * 2048 + i];
.LBB0_524:
	s_waitcnt vmcnt(0)
	v_add_u32_e32 v6, s12, v2
	v_add_u32_e32 v8, s13, v3
	v_ashrrev_i32_e32 v7, 31, v6
	v_ashrrev_i32_e32 v9, 31, v8
	v_lshl_add_u64 v[6:7], v[6:7], 2, s[24:25]
	v_lshl_add_u64 v[8:9], v[8:9], 2, s[24:25]
	global_load_dword v5, v[6:7], off
	global_load_dword v10, v[8:9], off
	global_load_dword v11, v[6:7], off offset:2048
	global_load_dword v12, v[8:9], off offset:2048
	v_add_u32_e32 v6, s12, v2
	v_add_u32_e32 v8, s13, v3
	v_add_u32_e32 v6, 0x400, v6
	v_add_u32_e32 v8, 0x400, v8
	v_ashrrev_i32_e32 v7, 31, v6
	v_ashrrev_i32_e32 v9, 31, v8
	v_lshl_add_u64 v[6:7], v[6:7], 2, s[24:25]
	v_lshl_add_u64 v[8:9], v[8:9], 2, s[24:25]
	global_load_dword v13, v[6:7], off
	global_load_dword v14, v[8:9], off
	global_load_dword v15, v[6:7], off offset:2048
	global_load_dword v16, v[8:9], off offset:2048
	s_or_b64 exec, exec, s[4:5]
	s_mov_b64 s[4:5], 0
	s_and_saveexec_b64 s[12:13], s[10:11]
	s_mov_b64 s[4:5], exec
	v_lshlrev_b32_e32 v0, 2, v221
	s_or_b64 exec, exec, s[12:13]
	s_orn2_b64 s[4:5], s[4:5], exec
	v_mov_b32_e32 v2, v221

; template <int DQK, int DV, int MODE> ...
;     ...
;   bf16_t* Qs = (bf16_t*)(smem + ATT_Q_OFF) + (w * 2 * NKS) * 512 + lane * 8;
; #pragma unroll
;   for (int qi = 0; qi < 2; ++qi)
; #pragma unroll
;     for (int ks = 0; ks < NKS; ++ks)
;       *(bf16x8*)(Qs + (qi * NKS + ks) * 512) = *(const bf16x8*)(Qp + (unsigned)((w * 32 + qi * 16 + fr) * qrs + ks * 32 + fq * 8));
; #pragma unroll
;   for (int qi = 0; qi < 2; ++qi) {
;     mrow[qi] = -1e30f; lrow[qi] = 0.f;
; #pragma unroll
;     for (int dt = 0; dt < NDT; ++dt) O[qi][dt] = (f32x4){0.f, 0.f, 0.f, 0.f};
;   }
;   int wkb, wke;
;   if (MODE == 0) { wkb = max(kt_begin, w >> 1); wke = (w * 32 + 159) / 64 + 1; }
;   else { wkb = 0; wke = (qpos0 + w * 32 + 31) / 64 + 1; }
;   u32x4 rk[NKC], rv[NVC];
;   auto gload = [&](int kt) {
; #pragma unroll
;     for (int i = 0; i < NKC; ++i) { const int c = tid + 256 * i, key = c / KCH, part = c % KCH; rk[i] = *(const u32x4*)(Kp + (unsigned)((kt * 64 + key) * krs + part * 8)); }
;     if (MODE == 0) {
; #pragma unroll
;       for (int i = 0; i < NVC; ++i) { const int c = tid + 256 * i, key = c >> 3, part = c & 7; rv[i] = *(const u32x4*)(Vp + (unsigned)((kt * 64 + key) * vrs + part * 8)); }
;     } else {
; #pragma unroll
;       for (int i = 0; i < NVC; ++i) { const int c = tid + 256 * i, dv = c >> 3, kc = c & 7; rv[i] = *(const u32x4*)(Vp + (unsigned)(dv * vrs + kt * 64 + kc * 8)); }
;     }
;   };
;   auto sstore = [&]() {
; #pragma unroll
;     for (int i = 0; i < NKC; ++i) { const int c = tid + 256 * i, key = c / KCH, part = c % KCH; *(u32x4*)(Ks + key * KST + part * 8) = rk[i]; }
;     if (MODE == 0) {
; #pragma unroll
;       for (int i = 0; i < NVC; ++i) {
;         const int c = tid + 256 * i, key = c >> 3, part = c & 7;
;         const int pos = (key & 32) + ((key >> 2) & 3) * 8 + ((key >> 4) & 1) * 4 + (key & 3);
; #pragma unroll
;     ...
;     const long tok0 = (long)b * SEQ + qb * 128;
;     const bf16_t* Vp = p.vtB + (size_t)((b * 4 + h) * 128) * SEQ;
;     const int kt_end = (qb * 128 + 127) / 64 + 1;
;     f32x4 O[2][8]; float mr[2], lr[2];
;     flash_block<64, 128, 1>(p.qkB + tok0 * 1024 + h * 128 + mp * 64, 1024, p.qkB + (long)b * SEQ * 1024 + 512 + h * 128 + mp * 64, 1024, Vp, SEQ, 0, kt_end,
;                             qb * 128, 0, 0.125f * LOG2E, smem, O, mr, lr, tid);
.LBB0_531:
	s_or_b64 exec, exec, s[0:1]
	s_lshl_b32 s0, s18, 6
	s_and_b32 s2, s0, 0xffffff80
	s_sub_i32 s3, 0x1f80, s2
	v_readlane_b32 s0, v252, 12
	s_add_i32 s74, s3, s0
	s_sub_i32 s0, 0x1fc0, s2
	s_and_b32 s22, s18, 1
	s_lshr_b32 s23, s0, 6
	s_lshl_b64 s[0:1], s[74:75], 11
	v_readlane_b32 s4, v252, 23
	s_add_u32 s0, s4, s0
	v_readlane_b32 s4, v252, 24
	s_addc_u32 s1, s4, s1
	s_lshl_b32 s4, s22, 7
	s_add_u32 s0, s0, s4
	s_addc_u32 s1, s1, 0
	v_lshl_add_u64 v[90:91], v[140:141], 1, s[0:1]
	v_lshl_add_u64 v[98:99], v[142:143], 1, s[0:1]
	v_lshl_add_u64 v[102:103], v[144:145], 1, s[0:1]
	global_load_dwordx4 v[94:97], v[90:91], off offset:64
	global_load_dwordx4 v[90:93], v[90:91], off
	global_load_dwordx4 v[98:101], v[98:99], off
	global_load_dwordx4 v[102:105], v[102:103], off
	s_waitcnt vmcnt(4)
	ds_write2st64_b32 v4, v5, v10 offset1:4
	ds_write2st64_b32 v4, v11, v12 offset0:8 offset1:12
	ds_write2st64_b32 v4, v13, v14 offset0:16 offset1:20
	ds_write2st64_b32 v4, v15, v16 offset0:24 offset1:28
	v_readlane_b32 s5, v252, 41
	s_add_u32 s18, s5, s4
	v_readlane_b32 s4, v252, 42
	s_addc_u32 s19, s4, 0
	v_add_u32_e32 v226, s3, v212
	v_ashrrev_i32_e32 v0, 31, v226
	v_lshrrev_b32_e32 v0, 26, v0
	v_mov_b32_e32 v12, v1
	v_mov_b32_e32 v13, v1
	v_add3_u32 v0, v0, v226, 31
	v_mov_b32_e32 v10, v1
	v_mov_b32_e32 v11, v1
	v_mov_b64_e32 v[24:25], v[12:13]
	v_mov_b64_e32 v[36:37], v[12:13]
	v_mov_b64_e32 v[40:41], v[12:13]
	v_mov_b64_e32 v[44:45], v[12:13]
	v_mov_b64_e32 v[48:49], v[12:13]
	v_mov_b64_e32 v[52:53], v[12:13]
	v_mov_b64_e32 v[56:57], v[12:13]
	v_mov_b64_e32 v[60:61], v[12:13]
	v_mov_b64_e32 v[64:65], v[12:13]
	v_mov_b64_e32 v[68:69], v[12:13]
	v_mov_b64_e32 v[72:73], v[12:13]
	v_mov_b64_e32 v[76:77], v[12:13]
	v_mov_b64_e32 v[80:81], v[12:13]
	v_mov_b64_e32 v[84:85], v[12:13]
	v_mov_b64_e32 v[88:89], v[12:13]
	v_ashrrev_i32_e32 v227, 6, v0
	v_add_u32_e32 v228, 0x3800, v214
	v_add_u32_e32 v229, 0x3800, v215
	v_add_u32_e32 v230, 0x3800, v219
	v_add_u32_e32 v231, 0x3800, v220
	v_subrev_u32_e32 v232, s2, v223
	s_add_i32 s24, s23, 1
	s_mov_b32 s25, 0
	v_mov_b32_e32 v234, 0xf149f2ca
	v_mov_b32_e32 v233, 0
	s_mov_b32 s26, 63
	v_mov_b32_e32 v0, v225
	v_mov_b32_e32 v164, v224
	v_mov_b64_e32 v[22:23], v[10:11]
	v_mov_b64_e32 v[34:35], v[10:11]
	v_mov_b64_e32 v[38:39], v[10:11]
	v_mov_b64_e32 v[42:43], v[10:11]
	v_mov_b64_e32 v[46:47], v[10:11]
	v_mov_b64_e32 v[50:51], v[10:11]
	v_mov_b64_e32 v[54:55], v[10:11]
	v_mov_b64_e32 v[58:59], v[10:11]
	v_mov_b64_e32 v[62:63], v[10:11]
	v_mov_b64_e32 v[66:67], v[10:11]
	v_mov_b64_e32 v[70:71], v[10:11]
	v_mov_b64_e32 v[74:75], v[10:11]
	v_mov_b64_e32 v[78:79], v[10:11]
	v_mov_b64_e32 v[82:83], v[10:11]
	v_mov_b64_e32 v[86:87], v[10:11]
	v_mov_b32_e32 v235, 0
	v_mov_b32_e32 v236, 0xf149f2ca
	v_lshl_add_u64 v[6:7], v[148:149], 1, s[18:19]
	v_lshl_add_u64 v[2:3], v[146:147], 1, s[18:19]
	global_load_dwordx4 v[2:5], v[2:3], off offset:1024
	s_nop 0
	global_load_dwordx4 v[6:9], v[6:7], off offset:1024
	s_nop 0
	global_load_dwordx4 v[14:17], v[154:155], off
	global_load_dwordx4 v[18:21], v[156:157], off
	global_load_dwordx4 v[26:29], v[158:159], off
	global_load_dwordx4 v[30:33], v[160:161], off
	s_waitcnt vmcnt(9)
	ds_write_b128 v129, v[94:97] offset:44096
	s_waitcnt vmcnt(8)
	ds_write_b128 v129, v[90:93] offset:43072
	s_waitcnt vmcnt(7)
	ds_write_b128 v129, v[98:101] offset:45120
	s_waitcnt vmcnt(6)
	ds_write_b128 v129, v[102:105] offset:46144
	s_waitcnt lgkmcnt(0)
	s_barrier
	s_waitcnt vmcnt(5)
	ds_write_b128 v205, v[2:5]
	s_waitcnt vmcnt(4)
	ds_write_b128 v206, v[6:9]
	s_waitcnt vmcnt(3)
	ds_write2_b64 v228, v[14:15], v[16:17] offset1:2
	s_waitcnt vmcnt(2)
	ds_write2_b64 v229, v[18:19], v[20:21] offset1:2
	s_waitcnt vmcnt(1)
	ds_write2_b64 v230, v[26:27], v[28:29] offset1:2
	s_waitcnt vmcnt(0)
	ds_write2_b64 v231, v[30:31], v[32:33] offset1:2
	s_waitcnt lgkmcnt(0)
	s_barrier
	s_branch .LBB0_533
